# DIFF attention units: two barriers per key tile with waves 4-7 one barrier behind waves 0-3 (QK+max of one wave overlaps exp+PV of its SIMD partner), LDS-DMA look-ahead 3->2 tiles
# speedup vs baseline: 1.0281x; 1.0281x over previous
; template <int MODE>
; __device__ __forceinline__ void flash_unit(ArgsP A, int l, int b, int h, int qb, unsigned char* lds) {
;     ...
;     } else if (MODE == 1) {
;         const float csc = 0.125f * LOG2E;
;         const bf16_t* qp = PROJ + (size_t)qrow * INWP + C_DQ + 128 * h + 64 * map + 8 * hh;
; #pragma unroll
;         for (int s = 0; s < NS; ++s) qf[s] = scale8(*(const u32x4*)(qp + 16 * s), csc);
;     } else {
;         const bf16_t* qp = PROJ + (size_t)qrow * INWP + C_RQ + 64 * h + 8 * hh;
; #pragma unroll
;         for (int s = 0; s < NS; ++s) qf[s] = __builtin_bit_cast(bf16x8, *(const u32x4*)(qp + 16 * s));
;     }
;     int posq = 0, qmin = 0; float bfar = 0.f;
;     if (MODE == 1) {
;         const int* pos = (const int*)A->in[2];
;         if (tid < 129) { int n = tid; int bucket;
;             if (n < 16) bucket = n; else { const float nf = (float)n; int lg = 16 + (int)(logf(nf / 16.f) / 2.0794415416798357f * 16.f); bucket = lg < 31 ? lg : 31; }
;             if (tid == 128) bucket = 31;
;             btab[tid] = A->in[3][bucket * 4 + h] * LOG2E; }
;         posq = pos[qrow];
;         int mn = posq;
; #pragma unroll
;         for (int o = 1; o < 64; o <<= 1) { const int other = __shfl_xor(mn, o); mn = other < mn ? other : mn; }
;         qmin = mn;
;     }
;     ...
;     int kbase[4];
; #pragma unroll
;     for (int bsel = 0; bsel < 4; ++bsel) { const int ch = 2 * bsel + hh + (MODE == 1 ? 8 * map : 0), xr = (MODE == 1) ? (q32 & 15) : ((q32 >> 1) & 7); kbase[bsel] = (q32 * KCH + (ch ^ xr)) * 16; }
;     auto dma_tile = [&](int t) {
;         const int kr0 = rowbase + 64 * t;
;         const int slot = t % NBUF; const unsigned kb_ = lds0 + slot * KBYTES, vb_ = lds0 + NBUF * KBYTES + slot * VBYTES;
; #pragma unroll
;         for (int i = 0; i < NKI; ++i) { const int piece = wave + 8 * i, p = 64 * piece + lane, key = p / KCH, cs = p % KCH;
;             const int ch = cs ^ (MODE == 1 ? (key & 15) : ((key >> 1) & 7)); const bf16_t* src;
;             if (MODE == 0) src = (ch < 16) ? KVM + (size_t)(kr0 + key) * 1024 + 256 * h + 8 * ch : PROJ + (size_t)(kr0 + key) * INWP + C_KR + 8 * (ch - 16);
;             else if (MODE == 1) src = PROJ + (size_t)(kr0 + key) * INWP + C_DK + 128 * h + 8 * ch;
;             else src = PROJ + (size_t)(kr0 + key) * INWP + C_RK + 64 * h + 8 * ch;
.LBB0_806:
	s_or_b64 exec, exec, s[4:5]
	s_waitcnt vmcnt(3)
	v_lshlrev_b32_e32 v20, 16, v12
	v_and_b32_e32 v21, 0xffff0000, v12
	s_mov_b32 s6, 0x3e38aa3b
	v_lshlrev_b32_e32 v12, 16, v13
	v_and_b32_e32 v13, 0xffff0000, v13
	v_pk_mul_f32 v[12:13], v[12:13], s[6:7] op_sel_hi:[1,0]
	v_mov_b32_e32 v157, v177
	v_cvt_pk_bf16_f32 v97, v12, v13
	v_lshlrev_b32_e32 v12, 16, v14
	v_and_b32_e32 v13, 0xffff0000, v14
	v_pk_mul_f32 v[12:13], v[12:13], s[6:7] op_sel_hi:[1,0]
	v_pk_mul_f32 v[20:21], v[20:21], s[6:7] op_sel_hi:[1,0]
	v_cvt_pk_bf16_f32 v98, v12, v13
	v_lshlrev_b32_e32 v12, 16, v15
	v_and_b32_e32 v13, 0xffff0000, v15
	v_pk_mul_f32 v[12:13], v[12:13], s[6:7] op_sel_hi:[1,0]
	v_and_b32_e32 v112, 63, v18
	v_cvt_pk_bf16_f32 v99, v12, v13
	s_waitcnt vmcnt(2)
	v_lshlrev_b32_e32 v12, 16, v8
	v_and_b32_e32 v13, 0xffff0000, v8
	v_lshlrev_b32_e32 v8, 16, v9
	v_and_b32_e32 v9, 0xffff0000, v9
	v_pk_mul_f32 v[8:9], v[8:9], s[6:7] op_sel_hi:[1,0]
	v_pk_mul_f32 v[12:13], v[12:13], s[6:7] op_sel_hi:[1,0]
	v_cvt_pk_bf16_f32 v101, v8, v9
	v_lshlrev_b32_e32 v8, 16, v10
	v_and_b32_e32 v9, 0xffff0000, v10
	v_pk_mul_f32 v[8:9], v[8:9], s[6:7] op_sel_hi:[1,0]
	v_cvt_pk_bf16_f32 v96, v20, v21
	v_cvt_pk_bf16_f32 v102, v8, v9
	v_lshlrev_b32_e32 v8, 16, v11
	v_and_b32_e32 v9, 0xffff0000, v11
	v_pk_mul_f32 v[8:9], v[8:9], s[6:7] op_sel_hi:[1,0]
	v_cvt_pk_bf16_f32 v100, v12, v13
	v_cvt_pk_bf16_f32 v103, v8, v9
	s_waitcnt vmcnt(1)
	v_lshlrev_b32_e32 v8, 16, v4
	v_and_b32_e32 v9, 0xffff0000, v4
	v_lshlrev_b32_e32 v4, 16, v5
	v_and_b32_e32 v5, 0xffff0000, v5
	v_pk_mul_f32 v[4:5], v[4:5], s[6:7] op_sel_hi:[1,0]
	v_pk_mul_f32 v[8:9], v[8:9], s[6:7] op_sel_hi:[1,0]
	v_cvt_pk_bf16_f32 v105, v4, v5
	v_lshlrev_b32_e32 v4, 16, v6
	v_and_b32_e32 v5, 0xffff0000, v6
	v_pk_mul_f32 v[4:5], v[4:5], s[6:7] op_sel_hi:[1,0]
	v_cvt_pk_bf16_f32 v104, v8, v9
	v_cvt_pk_bf16_f32 v106, v4, v5
	v_lshlrev_b32_e32 v4, 16, v7
	v_and_b32_e32 v5, 0xffff0000, v7
	v_pk_mul_f32 v[4:5], v[4:5], s[6:7] op_sel_hi:[1,0]
	s_and_b32 s5, s24, 0xffffffc0
	v_cvt_pk_bf16_f32 v107, v4, v5
	s_waitcnt vmcnt(0)
	v_lshlrev_b32_e32 v4, 16, v0
	v_and_b32_e32 v5, 0xffff0000, v0
	v_lshlrev_b32_e32 v0, 16, v1
	v_and_b32_e32 v1, 0xffff0000, v1
	v_pk_mul_f32 v[0:1], v[0:1], s[6:7] op_sel_hi:[1,0]
	v_pk_mul_f32 v[4:5], v[4:5], s[6:7] op_sel_hi:[1,0]
	v_cvt_pk_bf16_f32 v109, v0, v1
	v_lshlrev_b32_e32 v0, 16, v2
	v_and_b32_e32 v1, 0xffff0000, v2
	v_pk_mul_f32 v[0:1], v[0:1], s[6:7] op_sel_hi:[1,0]
	v_xor_b32_e32 v2, 2, v179
	v_cvt_pk_bf16_f32 v110, v0, v1
	v_lshlrev_b32_e32 v0, 16, v3
	v_and_b32_e32 v1, 0xffff0000, v3
	v_pk_mul_f32 v[0:1], v[0:1], s[6:7] op_sel_hi:[1,0]
	v_cvt_pk_bf16_f32 v108, v4, v5
	v_cvt_pk_bf16_f32 v111, v0, v1
	s_waitcnt lgkmcnt(0)
	v_lshl_add_u64 v[0:1], v[156:157], 2, s[2:3]
	global_load_dword v124, v[0:1], off
	v_and_b32_e32 v0, 64, v179
	v_add_u32_e32 v0, 64, v0
	v_xor_b32_e32 v1, 1, v179
	v_cmp_lt_i32_e32 vcc, v1, v0
	v_or_b32_e32 v4, s5, v112
	s_nop 0
	v_cndmask_b32_e32 v1, v179, v1, vcc
	v_lshlrev_b32_e32 v1, 2, v1
	v_cmp_lt_i32_e32 vcc, v2, v0
	s_add_i32 s5, s14, 8
	v_lshl_or_b32 v5, s5, 6, v112
	v_cndmask_b32_e32 v2, v179, v2, vcc
	v_lshlrev_b32_e32 v2, 2, v2
	s_lshl_b32 s26, s5, 10
	s_ashr_i32 s6, s24, 4
	s_lshl_b32 s5, s5, 2
	s_lshl_b32 s4, s25, 7
	s_lshl_b32 s31, s14, 10
	s_and_b32 s25, s6, -8
	s_movk_i32 s6, 0x60
	s_and_b32 s34, s5, -8
	s_lshl_b32 s5, s16, 2
	s_add_u32 s36, s2, s5
	s_addc_u32 s37, s3, 0
	s_lshl_b32 s18, s4, 1
	s_cmp_lg_u32 16, -1
	s_mov_b64 s[20:21], 0x1980
	s_cselect_b32 s4, 16, 0
	s_mov_b64 s[22:23], 0x1d80
	s_add_i32 s5, s4, 0x10000
	v_mov_b32_e32 v119, v177
	v_mov_b32_e32 v113, v177
	s_waitcnt vmcnt(0)
	ds_bpermute_b32 v1, v1, v124
	s_waitcnt lgkmcnt(0)
	v_min_i32_e32 v1, v1, v124
	ds_bpermute_b32 v2, v2, v1
	s_waitcnt lgkmcnt(0)
	v_min_i32_e32 v1, v2, v1
	v_xor_b32_e32 v2, 4, v179
	v_cmp_lt_i32_e32 vcc, v2, v0
	s_nop 1
	v_cndmask_b32_e32 v2, v179, v2, vcc
	v_lshlrev_b32_e32 v2, 2, v2
	ds_bpermute_b32 v2, v2, v1
	s_waitcnt lgkmcnt(0)
	v_min_i32_e32 v1, v2, v1
	v_xor_b32_e32 v2, 8, v179
	v_cmp_lt_i32_e32 vcc, v2, v0
	s_nop 1
	v_cndmask_b32_e32 v2, v179, v2, vcc
	v_lshlrev_b32_e32 v2, 2, v2
	ds_bpermute_b32 v2, v2, v1
	s_waitcnt lgkmcnt(0)
	v_min_i32_e32 v1, v2, v1
	v_xor_b32_e32 v2, 16, v179
	v_cmp_lt_i32_e32 vcc, v2, v0
	s_nop 1
	v_cndmask_b32_e32 v2, v179, v2, vcc
	v_lshlrev_b32_e32 v2, 2, v2
	ds_bpermute_b32 v2, v2, v1
	s_waitcnt lgkmcnt(0)
	v_min_i32_e32 v1, v2, v1
	v_xor_b32_e32 v2, 32, v179
	v_cmp_lt_i32_e32 vcc, v2, v0
	s_nop 1
	v_cndmask_b32_e32 v0, v179, v2, vcc
	v_lshlrev_b32_e32 v174, 2, v0
	ds_bpermute_b32 v0, v174, v1
	s_waitcnt lgkmcnt(0)
	v_min_i32_e32 v125, v0, v1
	v_mov_b32_e32 v0, v177
	v_lshlrev_b32_e32 v1, 3, v112
	v_ashrrev_i32_e32 v0, 31, v4
	v_lshrrev_b32_e32 v0, 28, v0
	v_add_u32_e32 v0, v4, v0
	v_ashrrev_i32_e32 v2, 4, v0
	v_and_b32_e32 v0, 0x1ffffff0, v0
	v_sub_u32_e32 v0, v4, v0
	v_bitop3_b32 v0, v2, v0, 15 bitop3:0x6c
	v_lshlrev_b32_e32 v114, 3, v0
	v_ashrrev_i32_e32 v0, 31, v5
	v_lshrrev_b32_e32 v0, 28, v0
	v_add_u32_e32 v0, v5, v0
	v_ashrrev_i32_e32 v3, 4, v0
	v_and_b32_e32 v0, 0x1ffffff0, v0
	v_and_b32_e32 v1, 24, v1
	v_sub_u32_e32 v0, v5, v0
	v_and_or_b32 v12, v4, s6, v1
	v_and_or_b32 v13, v5, s6, v1
	v_add_u32_e32 v126, s16, v2
	v_mov_b64_e32 v[4:5], s[10:11]
	v_ashrrev_i32_e32 v115, 31, v114
	v_mad_i64_i32 v[6:7], s[2:3], v126, s35, v[4:5]
	v_lshl_add_u64 v[6:7], v[6:7], 0, s[18:19]
	v_lshlrev_b64 v[8:9], 1, v[114:115]
	v_bitop3_b32 v0, v3, v0, 15 bitop3:0x6c
	v_lshl_add_u64 v[6:7], v[6:7], 0, v[8:9]
	v_lshlrev_b32_e32 v116, 3, v0
	v_lshl_add_u64 v[6:7], v[6:7], 0, s[20:21]
	s_add_i32 s2, s31, s4
	v_add_u32_e32 v127, s16, v3
	s_barrier
; template <int MODE>
; __device__ __forceinline__ void flash_unit(ArgsP A, int l, int b, int h, int qb, unsigned char* lds) {
;     ...
;     auto dma_tile = [&](int t) {
;         const int kr0 = rowbase + 64 * t;
;         const int slot = t % NBUF; const unsigned kb_ = lds0 + slot * KBYTES, vb_ = lds0 + NBUF * KBYTES + slot * VBYTES;
; #pragma unroll
;         for (int i = 0; i < NKI; ++i) { const int piece = wave + 8 * i, p = 64 * piece + lane, key = p / KCH, cs = p % KCH;
;             const int ch = cs ^ (MODE == 1 ? (key & 15) : ((key >> 1) & 7)); const bf16_t* src;
;             if (MODE == 0) src = (ch < 16) ? KVM + (size_t)(kr0 + key) * 1024 + 256 * h + 8 * ch : PROJ + (size_t)(kr0 + key) * INWP + C_KR + 8 * (ch - 16);
;             else if (MODE == 1) src = PROJ + (size_t)(kr0 + key) * INWP + C_DK + 128 * h + 8 * ch;
;             else src = PROJ + (size_t)(kr0 + key) * INWP + C_RK + 64 * h + 8 * ch;
;             glds16(src, (unsigned)__builtin_amdgcn_readfirstlane(kb_ + piece * 1024)); }
; #pragma unroll
;         for (int i = 0; i < 2; ++i) { const int piece = wave + 8 * i, p = 64 * piece + lane, st = p >> 5, key = 8 * (st >> 2) + ((p & 31) >> 2), col = 32 * (st & 3) + 8 * (p & 3); const bf16_t* src;
;             if (MODE == 0) src = KVM + (size_t)(kr0 + key) * 1024 + 256 * h + 128 + col;
;             else if (MODE == 1) src = PROJ + (size_t)(kr0 + key) * INWP + C_DV + 128 * h + col;
;             else src = PROJ + (size_t)(kr0 + key) * INWP + C_RV + 128 * h + col;
;             glds16(src, (unsigned)__builtin_amdgcn_readfirstlane(vb_ + piece * 1024)); }
;         if (MODE == 1) glds4((const int*)A->in[2] + rowbase + 64 * t + lane, (unsigned)__builtin_amdgcn_readfirstlane(lds0 + OFF_EXTRA + slot * 256));
;     };
;     f32x16 oacc[4];
; #pragma unroll
;     for (int c = 0; c < 4; ++c)
; #pragma unroll
;         for (int i = 0; i < 16; ++i) oacc[c][i] = 0.f;
;     float m_run = -INFINITY, l_run = 0.f;
; #pragma unroll
;     for (int s_ = 0; s_ < NS; ++s_) asm volatile("" : "+v"(qf[s_]));
;     asm volatile("" : "+v"(posq), "+v"(qmin), "+v"(lg2));
;     __syncthreads();
; #pragma unroll
;     for (int i = 0; i < NBUF - 1; ++i) if (i < ntile) dma_tile(i);
	v_ashrrev_i32_e32 v117, 31, v116
	s_mov_b32 s3, m0
	s_mov_b32 m0, s2
	s_nop 0
	global_load_lds_dwordx4 v[6:7], off
	s_mov_b32 m0, s3
	v_lshlrev_b64 v[10:11], 1, v[116:117]
	v_mad_i64_i32 v[6:7], s[2:3], v127, s35, v[4:5]
	v_lshl_add_u64 v[6:7], v[6:7], 0, s[18:19]
	v_bfe_u32 v0, v18, 2, 3
	v_lshl_add_u64 v[6:7], v[6:7], 0, v[10:11]
	v_lshl_add_u64 v[6:7], v[6:7], 0, s[20:21]
	v_or_b32_e32 v14, s16, v0
	s_add_i32 s2, s26, s4
	s_mov_b32 s3, m0
	s_mov_b32 m0, s2
	s_nop 0
	global_load_lds_dwordx4 v[6:7], off
	s_mov_b32 m0, s3
	v_add_u32_e32 v6, s25, v14
	v_mad_i64_i32 v[6:7], s[2:3], v6, s35, v[4:5]
	v_lshl_add_u64 v[6:7], v[6:7], 0, s[18:19]
	v_lshlrev_b32_e32 v176, 1, v12
	v_lshl_add_u64 v[6:7], v[6:7], 0, v[176:177]
	v_lshl_add_u64 v[6:7], v[6:7], 0, s[22:23]
	s_add_i32 s2, s31, s5
	s_mov_b32 s3, m0
	s_mov_b32 m0, s2
	s_nop 0
	global_load_lds_dwordx4 v[6:7], off
	s_mov_b32 m0, s3
	v_add_u32_e32 v6, s34, v14
	v_mad_i64_i32 v[6:7], s[2:3], v6, s35, v[4:5]
	v_lshl_add_u64 v[6:7], v[6:7], 0, s[18:19]
	v_lshlrev_b32_e32 v118, 1, v13
	v_lshl_add_u64 v[6:7], v[6:7], 0, v[118:119]
	v_lshl_add_u64 v[6:7], v[6:7], 0, s[22:23]
	s_add_i32 s2, s26, s5
	s_or_b32 s5, s16, 64
	s_mov_b32 s3, m0
	s_mov_b32 m0, s2
	s_nop 0
	global_load_lds_dwordx4 v[6:7], off
	s_mov_b32 m0, s3
	v_lshlrev_b32_e32 v6, 2, v112
	v_mov_b32_e32 v7, v177
	s_add_i32 s2, s4, 0x20000
	v_add_u32_e32 v12, s5, v2
	v_lshl_add_u64 v[6:7], s[36:37], 0, v[6:7]
	s_mov_b32 s3, m0
	s_mov_b32 m0, s2
	s_nop 0
	global_load_lds_dword v[6:7], off
	s_mov_b32 m0, s3
	s_add_i32 s6, s4, 0x4000
	v_mad_i64_i32 v[12:13], s[2:3], v12, s35, v[4:5]
	v_lshl_add_u64 v[12:13], v[12:13], 0, s[18:19]
	v_lshl_add_u64 v[8:9], v[12:13], 0, v[8:9]
	v_lshl_add_u64 v[8:9], v[8:9], 0, s[20:21]
	s_add_i32 s2, s31, s6
	s_mov_b32 s3, m0
	s_mov_b32 m0, s2
	s_nop 0
	global_load_lds_dwordx4 v[8:9], off
	s_mov_b32 m0, s3
	v_add_u32_e32 v8, s5, v3
	v_mad_i64_i32 v[8:9], s[2:3], v8, s35, v[4:5]
	v_lshl_add_u64 v[8:9], v[8:9], 0, s[18:19]
	v_lshl_add_u64 v[8:9], v[8:9], 0, v[10:11]
	v_lshl_add_u64 v[8:9], v[8:9], 0, s[20:21]
	v_or_b32_e32 v10, s5, v0
	s_add_i32 s2, s26, s6
	s_mov_b32 s3, m0
	s_mov_b32 m0, s2
	s_nop 0
	global_load_lds_dwordx4 v[8:9], off
	s_mov_b32 m0, s3
	v_add_u32_e32 v8, s25, v10
	v_mad_i64_i32 v[8:9], s[2:3], v8, s35, v[4:5]
	v_lshl_add_u64 v[8:9], v[8:9], 0, s[18:19]
	v_lshl_add_u64 v[8:9], v[8:9], 0, v[176:177]
	v_lshl_add_u64 v[8:9], v[8:9], 0, s[22:23]
	s_add_i32 s5, s4, 0x14000
	s_add_i32 s2, s31, s5
	s_mov_b32 s3, m0
	s_mov_b32 m0, s2
	s_nop 0
	global_load_lds_dwordx4 v[8:9], off
	s_mov_b32 m0, s3
	v_add_u32_e32 v8, s34, v10
	v_mad_i64_i32 v[4:5], s[2:3], v8, s35, v[4:5]
	v_lshl_add_u64 v[4:5], v[4:5], 0, s[18:19]
	v_lshl_add_u64 v[4:5], v[4:5], 0, v[118:119]
	v_lshl_add_u64 v[4:5], v[4:5], 0, s[22:23]
	s_add_i32 s2, s26, s5
	s_mov_b32 s3, m0
	s_mov_b32 m0, s2
	s_nop 0
	global_load_lds_dwordx4 v[4:5], off
	s_mov_b32 m0, s3
	s_mov_b64 s[2:3], 0x100
	v_lshl_add_u64 v[4:5], v[6:7], 0, s[2:3]
	s_add_i32 s4, s4, 0x20100
	s_mov_b32 s2, m0
	s_mov_b32 m0, s4
	s_nop 0
	global_load_lds_dword v[4:5], off
	s_mov_b32 m0, s2
	s_cmp_eq_u32 s17, 31
	s_branch .LBB0_808
	s_or_b32 s4, s16, 0x80
	v_add_u32_e32 v2, s4, v2
	v_mov_b64_e32 v[4:5], s[10:11]
	s_cmp_lg_u32 16, -1
	v_mad_i64_i32 v[6:7], s[2:3], v2, s35, v[4:5]
	s_cselect_b32 s5, 16, 0
	v_lshl_add_u64 v[6:7], v[6:7], 0, s[18:19]
	s_add_i32 s6, s5, 0x8000
	v_lshl_add_u64 v[6:7], v[114:115], 1, v[6:7]
	s_add_i32 s2, s31, s6
	v_add_u32_e32 v2, s4, v3
	v_lshl_add_u64 v[6:7], v[6:7], 0, s[20:21]
	s_mov_b32 s3, m0
	s_mov_b32 m0, s2
	s_nop 0
	global_load_lds_dwordx4 v[6:7], off
	s_mov_b32 m0, s3
	v_or_b32_e32 v6, s4, v0
	v_mad_i64_i32 v[2:3], s[2:3], v2, s35, v[4:5]
	v_lshl_add_u64 v[2:3], v[2:3], 0, s[18:19]
	v_lshl_add_u64 v[2:3], v[116:117], 1, v[2:3]
	v_lshl_add_u64 v[2:3], v[2:3], 0, s[20:21]
	s_add_i32 s2, s26, s6
	s_mov_b32 s3, m0
	s_mov_b32 m0, s2
	s_nop 0
	global_load_lds_dwordx4 v[2:3], off
	s_mov_b32 m0, s3
	v_add_u32_e32 v2, s25, v6
	v_mad_i64_i32 v[2:3], s[2:3], v2, s35, v[4:5]
	v_lshl_add_u64 v[2:3], v[2:3], 0, s[18:19]
	v_lshl_add_u64 v[2:3], v[2:3], 0, v[176:177]
	s_mov_b64 s[6:7], 0x1d80
	v_lshl_add_u64 v[2:3], v[2:3], 0, s[6:7]
	s_add_i32 s4, s5, 0x18000
	s_add_i32 s2, s31, s4
	s_mov_b32 s3, m0
	s_mov_b32 m0, s2
	s_nop 0
	global_load_lds_dwordx4 v[2:3], off
	s_mov_b32 m0, s3
	v_add_u32_e32 v2, s34, v6
	v_mad_i64_i32 v[2:3], s[2:3], v2, s35, v[4:5]
	v_lshl_add_u64 v[2:3], v[2:3], 0, s[18:19]
	v_lshl_add_u64 v[2:3], v[2:3], 0, v[118:119]
	v_lshl_add_u64 v[2:3], v[2:3], 0, s[6:7]
	s_add_i32 s2, s26, s4
	s_mov_b32 s3, m0
	s_mov_b32 m0, s2
	s_nop 0
	global_load_lds_dwordx4 v[2:3], off
	s_mov_b32 m0, s3
	v_lshl_add_u64 v[2:3], v[112:113], 2, s[36:37]
	s_mov_b64 s[2:3], 0x200
	v_lshl_add_u64 v[2:3], v[2:3], 0, s[2:3]
	s_add_i32 s5, s5, 0x20200
	s_mov_b32 s2, m0
	s_mov_b32 m0, s5
	s_nop 0
	global_load_lds_dword v[2:3], off
	s_mov_b32 m0, s2
; __device__ __forceinline__ int crow(int i, int hh) { return (i & 3) + 8 * (i >> 2) + 4 * hh; }
; template <int MODE>
; __device__ __forceinline__ void flash_unit(ArgsP A, int l, int b, int h, int qb, unsigned char* lds) {
;     ...
;     f32x16 oacc[4];
; #pragma unroll
;     for (int c = 0; c < 4; ++c)
; #pragma unroll
;         for (int i = 0; i < 16; ++i) oacc[c][i] = 0.f;
;     float m_run = -INFINITY, l_run = 0.f;
; #pragma unroll
;     for (int s_ = 0; s_ < NS; ++s_) asm volatile("" : "+v"(qf[s_]));
;     asm volatile("" : "+v"(posq), "+v"(qmin), "+v"(lg2));
;     __syncthreads();
; #pragma unroll
;     for (int i = 0; i < NBUF - 1; ++i) if (i < ntile) dma_tile(i);
;     for (int t = 0; t < ntile; ++t) {
;     ...
;                 if (diag) {
;                     asm volatile("" ::: "memory");
; #pragma unroll
;                     for (int kb = 0; kb < 2; ++kb)
; #pragma unroll
;                         for (int i = 0; i < 16; ++i) if (64 * t + 32 * kb + crow(i, hh) > qi) sacc[kb][i] = -INFINITY;
;                 }
.LBB0_808:
	s_lshl_b32 s2, s30, 3
	v_and_b32_e32 v3, 15, v18
	v_or_b32_e32 v2, s2, v17
	v_bitop3_b32 v4, s2, v3, v17 bitop3:0x36
	v_lshlrev_b32_e32 v131, 4, v4
	v_bitop3_b32 v4, v2, v3, 2 bitop3:0x36
	v_lshlrev_b32_e32 v132, 4, v4
	v_bitop3_b32 v4, v2, v3, 4 bitop3:0x36
	v_bitop3_b32 v2, v2, v3, 6 bitop3:0x36
	s_sub_i32 s2, 0x1000, s9
	v_lshlrev_b32_e32 v3, 4, v112
	v_lshlrev_b32_e32 v134, 4, v2
	s_lshr_b32 s27, s2, 6
	v_lshlrev_b32_e32 v2, 8, v17
	v_and_b32_e32 v3, 0xc0, v3
	s_add_i32 s2, 16, 0x10000
	v_add3_u32 v2, s2, v2, v3
	v_lshlrev_b32_e32 v3, 1, v112
	v_lshlrev_b32_e32 v172, 2, v17
	v_and_b32_e32 v3, 32, v3
	s_and_b32 s2, s8, 0x7fffffc0
	v_add3_u32 v135, v2, v3, v1
	v_or_b32_e32 v1, s2, v172
	v_or_b32_e32 v2, 2, v1
	v_cmp_gt_u32_e64 s[46:47], v2, v16
	v_or_b32_e32 v2, 3, v1
	v_cmp_gt_u32_e64 s[48:49], v2, v16
	v_or_b32_e32 v2, 8, v1
	v_cmp_gt_u32_e64 s[50:51], v2, v16
	v_or_b32_e32 v2, 9, v1
	v_cmp_gt_u32_e64 s[52:53], v2, v16
	v_or_b32_e32 v2, 10, v1
	v_cmp_gt_u32_e64 s[54:55], v2, v16
	v_or_b32_e32 v2, 11, v1
	v_cmp_gt_u32_e64 s[56:57], v2, v16
	v_or_b32_e32 v2, 16, v1
	v_cmp_gt_u32_e64 s[58:59], v2, v16
	v_or_b32_e32 v2, 17, v1
	v_cmp_gt_u32_e64 s[60:61], v2, v16
	v_or_b32_e32 v2, 18, v1
	v_cmp_gt_u32_e64 s[62:63], v2, v16
	v_or_b32_e32 v2, 19, v1
	v_cmp_gt_u32_e64 s[64:65], v2, v16
	v_or_b32_e32 v2, 24, v1
	v_cmp_gt_u32_e64 s[66:67], v2, v16
	v_or_b32_e32 v2, 25, v1
	v_cmp_gt_u32_e64 s[68:69], v2, v16
	v_or_b32_e32 v2, 26, v1
	v_cmp_gt_u32_e64 s[70:71], v2, v16
	v_or_b32_e32 v2, 27, v1
	v_cmp_gt_u32_e64 s[72:73], v2, v16
	v_or_b32_e32 v2, 32, v1
	v_cmp_gt_u32_e64 s[74:75], v2, v16
	v_or_b32_e32 v2, 33, v1
	v_cmp_gt_u32_e64 s[76:77], v2, v16
	v_or_b32_e32 v2, 34, v1
	v_cmp_gt_u32_e64 s[78:79], v2, v16
	v_or_b32_e32 v2, 35, v1
	v_cmp_gt_u32_e64 s[80:81], v2, v16
	v_or_b32_e32 v2, 40, v1
	v_cmp_gt_u32_e64 s[82:83], v2, v16
	v_or_b32_e32 v2, 41, v1
	v_cmp_gt_u32_e64 s[84:85], v2, v16
	v_or_b32_e32 v2, 42, v1
	v_cmp_gt_u32_e64 s[86:87], v2, v16
	v_or_b32_e32 v2, 43, v1
	v_cmp_gt_u32_e64 s[88:89], v2, v16
	v_or_b32_e32 v2, 48, v1
	v_cmp_gt_u32_e64 s[90:91], v2, v16
	v_or_b32_e32 v2, 49, v1
	v_cmp_gt_u32_e64 s[92:93], v2, v16
	v_or_b32_e32 v2, 50, v1
	v_cmp_gt_u32_e64 s[94:95], v2, v16
	v_or_b32_e32 v2, 51, v1
	v_cmp_gt_u32_e64 s[96:97], v2, v16
	v_or_b32_e32 v2, 56, v1
	v_cmp_gt_u32_e64 s[2:3], v2, v16
	v_or_b32_e32 v2, 57, v1
	v_cmp_gt_u32_e64 s[40:41], v1, v16
	v_cmp_lt_u32_e64 s[44:45], v1, v16
	v_cmp_gt_u32_e64 s[4:5], v2, v16
	v_or_b32_e32 v2, 58, v1
	v_or_b32_e32 v1, 59, v1
	s_add_i32 s17, s16, s34
	s_add_i32 s16, s16, s25
	v_mov_b32_e32 v48, v177
	v_mov_b32_e32 v49, v177
	v_lshlrev_b32_e32 v133, 4, v4
	s_lshr_b32 s42, s8, 6
	v_cmp_gt_u32_e64 s[6:7], v2, v16
	v_cmp_gt_u32_e64 s[8:9], v1, v16
	v_add_u32_e32 v136, s17, v0
	v_add_u32_e32 v137, s16, v0
	v_mov_b32_e32 v50, v177
	v_mov_b32_e32 v51, v177
	v_mov_b32_e32 v52, v177
	v_mov_b32_e32 v53, v177
	v_mov_b32_e32 v54, v177
	v_mov_b32_e32 v55, v177
	v_mov_b32_e32 v56, v177
	v_mov_b32_e32 v57, v177
	v_mov_b32_e32 v58, v177
	v_mov_b32_e32 v59, v177
	v_mov_b32_e32 v60, v177
	v_mov_b32_e32 v61, v177
	v_mov_b32_e32 v62, v177
	v_mov_b32_e32 v63, v177
	v_mov_b64_e32 v[32:33], v[48:49]
	v_mov_b64_e32 v[16:17], v[48:49]
	v_mov_b64_e32 v[0:1], v[48:49]
	v_lshlrev_b32_e32 v129, 8, v130
	s_movk_i32 s24, 0x80
	s_add_i32 s43, s27, -2
	s_mov_b32 s34, 0
	v_mov_b32_e32 v138, 0
	v_mov_b32_e32 v121, 0xff800000
	s_mov_b32 s16, -1
	v_mov_b64_e32 v[34:35], v[50:51]
	v_mov_b64_e32 v[36:37], v[52:53]
	v_mov_b64_e32 v[38:39], v[54:55]
	v_mov_b64_e32 v[40:41], v[56:57]
	v_mov_b64_e32 v[42:43], v[58:59]
	v_mov_b64_e32 v[44:45], v[60:61]
	v_mov_b64_e32 v[46:47], v[62:63]
	v_mov_b64_e32 v[18:19], v[50:51]
	v_mov_b64_e32 v[20:21], v[52:53]
	v_mov_b64_e32 v[22:23], v[54:55]
	v_mov_b64_e32 v[24:25], v[56:57]
	v_mov_b64_e32 v[26:27], v[58:59]
	v_mov_b64_e32 v[28:29], v[60:61]
	v_mov_b64_e32 v[30:31], v[62:63]
	v_mov_b64_e32 v[2:3], v[50:51]
	v_mov_b64_e32 v[4:5], v[52:53]
	v_mov_b64_e32 v[6:7], v[54:55]
	v_mov_b64_e32 v[8:9], v[56:57]
	v_mov_b64_e32 v[10:11], v[58:59]
	v_mov_b64_e32 v[12:13], v[60:61]
	v_mov_b64_e32 v[14:15], v[62:63]
	v_readfirstlane_b32 s20, v238
	s_cmp_lt_u32 s20, 0x100
	s_cbranch_scc1 .Ldf_nooff
	s_waitcnt vmcnt(5) lgkmcnt(0)
	s_barrier

; template <int MODE>
; __device__ __forceinline__ void flash_unit(ArgsP A, int l, int b, int h, int qb, unsigned char* lds) {
;     ...
;     for (int t = 0; t < ntile; ++t) {
;         {
;             const int later = (ntile - 1 - t) < (NBUF - 2) ? (ntile - 1 - t) : (NBUF - 2);
;             if (later <= 0) asm volatile("s_waitcnt vmcnt(0) lgkmcnt(0)\n\ts_barrier" ::: "memory");
;             else if (later == 1) asm volatile("s_waitcnt vmcnt(%0) lgkmcnt(0)\n\ts_barrier" :: "n"(OPS) : "memory");
;             else asm volatile("s_waitcnt vmcnt(%0) lgkmcnt(0)\n\ts_barrier" :: "n"(2 * OPS) : "memory");
;         }
;         if (t + NBUF - 1 < ntile) dma_tile(t + NBUF - 1);
.LBB0_809:
	s_add_i32 s20, s34, 2
	s_cmp_lt_u32 s20, s27
	s_cbranch_scc1 .Ldf_B5
	s_waitcnt vmcnt(0) lgkmcnt(0)
	s_barrier
	s_branch .Ldf_Bd
.Ldf_B5:
	s_waitcnt vmcnt(5) lgkmcnt(0)
	s_barrier

; template <int MODE>
; __device__ __forceinline__ void flash_unit(ArgsP A, int l, int b, int h, int qb, unsigned char* lds) {
;     ...
;     for (int t = 0; t < ntile; ++t) {
;         {
;             const int later = (ntile - 1 - t) < (NBUF - 2) ? (ntile - 1 - t) : (NBUF - 2);
;             if (later <= 0) asm volatile("s_waitcnt vmcnt(0) lgkmcnt(0)\n\ts_barrier" ::: "memory");
;             else if (later == 1) asm volatile("s_waitcnt vmcnt(%0) lgkmcnt(0)\n\ts_barrier" :: "n"(OPS) : "memory");
;             else asm volatile("s_waitcnt vmcnt(%0) lgkmcnt(0)\n\ts_barrier" :: "n"(2 * OPS) : "memory");
;         }
;         if (t + NBUF - 1 < ntile) dma_tile(t + NBUF - 1);
.LBB0_811:
	s_add_i32 s20, s34, 1
	s_cmp_lt_u32 s20, s27
	s_cbranch_scc1 .Ldf_A5
	s_waitcnt vmcnt(0) lgkmcnt(0)
	s_barrier
	s_branch .LBB0_813

; template <int MODE>
; __device__ __forceinline__ void flash_unit(ArgsP A, int l, int b, int h, int qb, unsigned char* lds) {
;     ...
;     for (int t = 0; t < ntile; ++t) {
;         {
;             const int later = (ntile - 1 - t) < (NBUF - 2) ? (ntile - 1 - t) : (NBUF - 2);
;             if (later <= 0) asm volatile("s_waitcnt vmcnt(0) lgkmcnt(0)\n\ts_barrier" ::: "memory");
;             else if (later == 1) asm volatile("s_waitcnt vmcnt(%0) lgkmcnt(0)\n\ts_barrier" :: "n"(OPS) : "memory");
;             else asm volatile("s_waitcnt vmcnt(%0) lgkmcnt(0)\n\ts_barrier" :: "n"(2 * OPS) : "memory");
;         }
;         if (t + NBUF - 1 < ntile) dma_tile(t + NBUF - 1);
.LBB0_813:
	s_add_i32 s17, s34, 2
	s_cmp_ge_u32 s17, s27
	s_cbranch_scc0 .LBB0_821

; template <int MODE>
; __device__ __forceinline__ void flash_unit(ArgsP A, int l, int b, int h, int qb, unsigned char* lds) {
;     ...
;     for (int t = 0; t < ntile; ++t) {
;         {
;             const int later = (ntile - 1 - t) < (NBUF - 2) ? (ntile - 1 - t) : (NBUF - 2);
;             if (later <= 0) asm volatile("s_waitcnt vmcnt(0) lgkmcnt(0)\n\ts_barrier" ::: "memory");
;             else if (later == 1) asm volatile("s_waitcnt vmcnt(%0) lgkmcnt(0)\n\ts_barrier" :: "n"(OPS) : "memory");
;             else asm volatile("s_waitcnt vmcnt(%0) lgkmcnt(0)\n\ts_barrier" :: "n"(2 * OPS) : "memory");
;         }
;         if (t + NBUF - 1 < ntile) dma_tile(t + NBUF - 1);
.Ldf_sB5:
	s_waitcnt vmcnt(5) lgkmcnt(0)
	s_barrier
	s_branch .LBB0_810

; template <int MODE>
; __device__ __forceinline__ void flash_unit(ArgsP A, int l, int b, int h, int qb, unsigned char* lds) {
;     ...
;     }
;     __syncthreads();
.LBB0_830:
	v_readfirstlane_b32 s20, v238
	s_cmp_ge_u32 s20, 0x100
	s_cbranch_scc1 .Ldf_nobal
	s_barrier
